# comb11 + conv LayerNorm tail: wave reductions through DPP / permlane swaps (no ds_bpermute round trips) and gain vectors staged once per unit in LDS
# speedup vs baseline: 1.0060x; 1.0016x over previous
; #define LAS __attribute__((address_space(3)))
; #define KIN(i) (*(const float* const __attribute__((address_space(4)))*)(kp + kz + 8 * (i)))
; __global__ void __launch_bounds__(NTHR, 2) fwd_megakernel(Args args) {
;     ...
;             for (int rr = 0; rr < 4; ++rr) { const int r = wave * 4 + rr; f32x4 x[4]; float s = 0.f;
; #pragma unroll
;                 for (int j = 0; j < 4; ++j) { x[j] = *(const LAS f32x4*)(Os + r * CCH + j * 256 + 4 * lane); s += (x[j][0] + x[j][1]) + (x[j][2] + x[j][3]); }
;                 const float mean = wave_sum(s) * (1.0f / CCH); float q = 0.f;
; #pragma unroll
;                 for (int j = 0; j < 4; ++j) { x[j] = x[j] - mean; q += (x[j][0] * x[j][0] + x[j][1] * x[j][1]) + (x[j][2] * x[j][2] + x[j][3] * x[j][3]); }
;                 const float rstd = rsqrtf(wave_sum(q) * (1.0f / CCH) + LN_EPS); float z2 = 0.f;
; #pragma unroll
;                 for (int j = 0; j < 4; ++j) { const f32x4 gg = *(const f32x4*)(KIN(I_CONV_LN_G) + j * 256 + 4 * lane), bb = *(const f32x4*)(KIN(I_CONV_LN_B) + j * 256 + 4 * lane);
;                     f32x4 y = x[j] * rstd * gg + bb;
.LBB0_562:
	v_lshlrev_b32_e32 v140, 4, v221
	v_add_u32_e32 v140, 0x20000, v140
	v_and_b32_e32 v141, 0xff, v221
	v_lshlrev_b32_e32 v141, 4, v141
	v_add_u32_e32 v141, 0x22000, v141
	ds_write_b128 v140, v[246:249]
	ds_write_b128 v141, v[250:253]
	s_waitcnt lgkmcnt(0)
	s_barrier
	v_add_u32_e32 v94, 0x20000, v219
	ds_read_b128 v[204:207], v94
	ds_read_b128 v[232:235], v94 offset:4096
	ds_read_b128 v[208:211], v94 offset:1024
	ds_read_b128 v[236:239], v94 offset:5120
	ds_read_b128 v[212:215], v94 offset:2048
	ds_read_b128 v[240:243], v94 offset:6144
	ds_read_b128 v[228:231], v94 offset:3072
	ds_read_b128 v[0:3], v94 offset:7168
	ds_read_b128 v[4:7], v94 offset:8192
	ds_read_b128 v[8:11], v94 offset:9216
	ds_read_b128 v[12:15], v94 offset:10240
	ds_read_b128 v[16:19], v94 offset:11264
	v_add_u32_e32 v98, s24, v219
	v_add_u32_e32 v99, s26, v219
	v_add_u32_e32 v100, s57, v219
	v_add_u32_e32 v101, s59, v219
	ds_read_b128 v[140:143], v98
	ds_read_b128 v[144:147], v98 offset:1024
	ds_read_b128 v[148:151], v98 offset:2048
	ds_read_b128 v[152:155], v98 offset:3072
	ds_read_b128 v[156:159], v99
	ds_read_b128 v[160:163], v99 offset:1024
	ds_read_b128 v[164:167], v99 offset:2048
	ds_read_b128 v[168:171], v99 offset:3072
	ds_read_b128 v[172:175], v100
	ds_read_b128 v[176:179], v100 offset:1024
	ds_read_b128 v[180:183], v100 offset:2048
	ds_read_b128 v[184:187], v100 offset:3072
	ds_read_b128 v[188:191], v101
	ds_read_b128 v[192:195], v101 offset:1024
	ds_read_b128 v[196:199], v101 offset:2048
	ds_read_b128 v[200:203], v101 offset:3072
	s_add_i32 s2, s56, s62
	s_ashr_i32 s3, s2, 31
	s_lshl_b64 s[2:3], s[2:3], 12
	v_lshl_add_u64 v[126:127], v[32:33], 0, s[2:3]
	s_add_i32 s2, s25, s62
	s_ashr_i32 s3, s2, 31
	s_lshl_b64 s[2:3], s[2:3], 12
	v_lshl_add_u64 v[128:129], v[32:33], 0, s[2:3]
	s_add_i32 s2, s27, s62
	s_ashr_i32 s3, s2, 31
	s_lshl_b64 s[2:3], s[2:3], 12
	v_lshl_add_u64 v[130:131], v[32:33], 0, s[2:3]
	s_add_i32 s2, s58, s62
	s_ashr_i32 s3, s2, 31
	s_lshl_b64 s[2:3], s[2:3], 12
	v_lshl_add_u64 v[132:133], v[32:33], 0, s[2:3]
	s_waitcnt lgkmcnt(0)
	v_add_f32_e32 v110, v140, v141
	v_add_f32_e32 v111, v142, v143
	v_add_f32_e32 v114, v156, v157
	v_add_f32_e32 v115, v158, v159
	v_add_f32_e32 v118, v172, v173
	v_add_f32_e32 v119, v174, v175
	v_add_f32_e32 v122, v188, v189
	v_add_f32_e32 v123, v190, v191
	v_add_f32_e32 v110, v110, v111
	v_add_f32_e32 v114, v114, v115
	v_add_f32_e32 v118, v118, v119
	v_add_f32_e32 v122, v122, v123
	v_mov_b32_e32 v94, v110
	v_mov_b32_e32 v95, v114
	v_mov_b32_e32 v96, v118
	v_mov_b32_e32 v97, v122
	v_add_f32_e32 v110, v144, v145
	v_add_f32_e32 v111, v146, v147
	v_add_f32_e32 v114, v160, v161
	v_add_f32_e32 v115, v162, v163
	v_add_f32_e32 v118, v176, v177
	v_add_f32_e32 v119, v178, v179
	v_add_f32_e32 v122, v192, v193
	v_add_f32_e32 v123, v194, v195
	v_add_f32_e32 v110, v110, v111
	v_add_f32_e32 v114, v114, v115
	v_add_f32_e32 v118, v118, v119
	v_add_f32_e32 v122, v122, v123
	v_add_f32_e32 v94, v94, v110
	v_add_f32_e32 v95, v95, v114
	v_add_f32_e32 v96, v96, v118
	v_add_f32_e32 v97, v97, v122
	v_add_f32_e32 v110, v148, v149
	v_add_f32_e32 v111, v150, v151
	v_add_f32_e32 v114, v164, v165
	v_add_f32_e32 v115, v166, v167
	v_add_f32_e32 v118, v180, v181
	v_add_f32_e32 v119, v182, v183
	v_add_f32_e32 v122, v196, v197
	v_add_f32_e32 v123, v198, v199
	v_add_f32_e32 v110, v110, v111
	v_add_f32_e32 v114, v114, v115
	v_add_f32_e32 v118, v118, v119
	v_add_f32_e32 v122, v122, v123
	v_add_f32_e32 v94, v94, v110
	v_add_f32_e32 v95, v95, v114
	v_add_f32_e32 v96, v96, v118
	v_add_f32_e32 v97, v97, v122
	v_add_f32_e32 v110, v152, v153
	v_add_f32_e32 v111, v154, v155
	v_add_f32_e32 v114, v168, v169
	v_add_f32_e32 v115, v170, v171
	v_add_f32_e32 v118, v184, v185
	v_add_f32_e32 v119, v186, v187
	v_add_f32_e32 v122, v200, v201
	v_add_f32_e32 v123, v202, v203
	v_add_f32_e32 v110, v110, v111
	v_add_f32_e32 v114, v114, v115
	v_add_f32_e32 v118, v118, v119
	v_add_f32_e32 v122, v122, v123
	v_add_f32_e32 v94, v94, v110
	v_add_f32_e32 v95, v95, v114
	v_add_f32_e32 v96, v96, v118
	v_add_f32_e32 v97, v97, v122
	s_nop 1
	v_add_f32_dpp v98, v94, v94 quad_perm:[1,0,3,2] row_mask:0xf bank_mask:0xf
	v_add_f32_dpp v99, v95, v95 quad_perm:[1,0,3,2] row_mask:0xf bank_mask:0xf
	v_add_f32_dpp v100, v96, v96 quad_perm:[1,0,3,2] row_mask:0xf bank_mask:0xf
	v_add_f32_dpp v101, v97, v97 quad_perm:[1,0,3,2] row_mask:0xf bank_mask:0xf
	v_mov_b32_e32 v94, v98
	v_mov_b32_e32 v95, v99
	v_mov_b32_e32 v96, v100
	v_mov_b32_e32 v97, v101
	s_nop 1
	v_add_f32_dpp v98, v94, v94 quad_perm:[2,3,0,1] row_mask:0xf bank_mask:0xf
	v_add_f32_dpp v99, v95, v95 quad_perm:[2,3,0,1] row_mask:0xf bank_mask:0xf
	v_add_f32_dpp v100, v96, v96 quad_perm:[2,3,0,1] row_mask:0xf bank_mask:0xf
	v_add_f32_dpp v101, v97, v97 quad_perm:[2,3,0,1] row_mask:0xf bank_mask:0xf
	v_mov_b32_e32 v94, v98
	v_mov_b32_e32 v95, v99
	v_mov_b32_e32 v96, v100
	v_mov_b32_e32 v97, v101
	s_nop 1
	v_add_f32_dpp v98, v94, v94 row_half_mirror row_mask:0xf bank_mask:0xf
	v_add_f32_dpp v99, v95, v95 row_half_mirror row_mask:0xf bank_mask:0xf
	v_add_f32_dpp v100, v96, v96 row_half_mirror row_mask:0xf bank_mask:0xf
	v_add_f32_dpp v101, v97, v97 row_half_mirror row_mask:0xf bank_mask:0xf
	v_mov_b32_e32 v94, v98
	v_mov_b32_e32 v95, v99
	v_mov_b32_e32 v96, v100
	v_mov_b32_e32 v97, v101
	s_nop 1
	v_add_f32_dpp v98, v94, v94 row_mirror row_mask:0xf bank_mask:0xf
	v_add_f32_dpp v99, v95, v95 row_mirror row_mask:0xf bank_mask:0xf
	v_add_f32_dpp v100, v96, v96 row_mirror row_mask:0xf bank_mask:0xf
	v_add_f32_dpp v101, v97, v97 row_mirror row_mask:0xf bank_mask:0xf
	v_mov_b32_e32 v94, v98
	v_mov_b32_e32 v95, v99
	v_mov_b32_e32 v96, v100
; __global__ void __launch_bounds__(NTHR, 2) fwd_megakernel(Args args) {
;     ...
;                 const float mean = wave_sum(s) * (1.0f / CCH); float q = 0.f;
; #pragma unroll
;                 for (int j = 0; j < 4; ++j) { x[j] = x[j] - mean; q += (x[j][0] * x[j][0] + x[j][1] * x[j][1]) + (x[j][2] * x[j][2] + x[j][3] * x[j][3]); }
;                 const float rstd = rsqrtf(wave_sum(q) * (1.0f / CCH) + LN_EPS); float z2 = 0.f;
	v_mov_b32_e32 v97, v101
	v_mov_b32_e32 v98, v94
	v_mov_b32_e32 v99, v95
	v_mov_b32_e32 v100, v96
	v_mov_b32_e32 v101, v97
	s_nop 1
	v_permlane16_swap_b32_e32 v94, v98
	v_permlane16_swap_b32_e32 v95, v99
	v_permlane16_swap_b32_e32 v96, v100
	v_permlane16_swap_b32_e32 v97, v101
	s_nop 1
	v_add_f32_e32 v94, v94, v98
	v_add_f32_e32 v95, v95, v99
	v_add_f32_e32 v96, v96, v100
	v_add_f32_e32 v97, v97, v101
	v_mov_b32_e32 v98, v94
	v_mov_b32_e32 v99, v95
	v_mov_b32_e32 v100, v96
	v_mov_b32_e32 v101, v97
	s_nop 1
	v_permlane32_swap_b32_e32 v94, v98
	v_permlane32_swap_b32_e32 v95, v99
	v_permlane32_swap_b32_e32 v96, v100
	v_permlane32_swap_b32_e32 v97, v101
	s_nop 1
	v_add_f32_e32 v94, v94, v98
	v_add_f32_e32 v95, v95, v99
	v_add_f32_e32 v96, v96, v100
	v_add_f32_e32 v97, v97, v101
	v_fmamk_f32 v140, v94, 0xba800000, v140
	v_fmamk_f32 v141, v94, 0xba800000, v141
	v_fmamk_f32 v142, v94, 0xba800000, v142
	v_fmamk_f32 v143, v94, 0xba800000, v143
	v_fmamk_f32 v144, v94, 0xba800000, v144
	v_fmamk_f32 v145, v94, 0xba800000, v145
	v_fmamk_f32 v146, v94, 0xba800000, v146
	v_fmamk_f32 v147, v94, 0xba800000, v147
	v_fmamk_f32 v148, v94, 0xba800000, v148
	v_fmamk_f32 v149, v94, 0xba800000, v149
	v_fmamk_f32 v150, v94, 0xba800000, v150
	v_fmamk_f32 v151, v94, 0xba800000, v151
	v_fmamk_f32 v152, v94, 0xba800000, v152
	v_fmamk_f32 v153, v94, 0xba800000, v153
	v_fmamk_f32 v154, v94, 0xba800000, v154
	v_fmamk_f32 v155, v94, 0xba800000, v155
	v_fmamk_f32 v156, v95, 0xba800000, v156
	v_fmamk_f32 v157, v95, 0xba800000, v157
	v_fmamk_f32 v158, v95, 0xba800000, v158
	v_fmamk_f32 v159, v95, 0xba800000, v159
	v_fmamk_f32 v160, v95, 0xba800000, v160
	v_fmamk_f32 v161, v95, 0xba800000, v161
	v_fmamk_f32 v162, v95, 0xba800000, v162
	v_fmamk_f32 v163, v95, 0xba800000, v163
	v_fmamk_f32 v164, v95, 0xba800000, v164
	v_fmamk_f32 v165, v95, 0xba800000, v165
	v_fmamk_f32 v166, v95, 0xba800000, v166
	v_fmamk_f32 v167, v95, 0xba800000, v167
	v_fmamk_f32 v168, v95, 0xba800000, v168
	v_fmamk_f32 v169, v95, 0xba800000, v169
	v_fmamk_f32 v170, v95, 0xba800000, v170
	v_fmamk_f32 v171, v95, 0xba800000, v171
	v_fmamk_f32 v172, v96, 0xba800000, v172
	v_fmamk_f32 v173, v96, 0xba800000, v173
	v_fmamk_f32 v174, v96, 0xba800000, v174
	v_fmamk_f32 v175, v96, 0xba800000, v175
	v_fmamk_f32 v176, v96, 0xba800000, v176
	v_fmamk_f32 v177, v96, 0xba800000, v177
	v_fmamk_f32 v178, v96, 0xba800000, v178
	v_fmamk_f32 v179, v96, 0xba800000, v179
	v_fmamk_f32 v180, v96, 0xba800000, v180
	v_fmamk_f32 v181, v96, 0xba800000, v181
	v_fmamk_f32 v182, v96, 0xba800000, v182
	v_fmamk_f32 v183, v96, 0xba800000, v183
	v_fmamk_f32 v184, v96, 0xba800000, v184
	v_fmamk_f32 v185, v96, 0xba800000, v185
	v_fmamk_f32 v186, v96, 0xba800000, v186
	v_fmamk_f32 v187, v96, 0xba800000, v187
	v_fmamk_f32 v188, v97, 0xba800000, v188
	v_fmamk_f32 v189, v97, 0xba800000, v189
	v_fmamk_f32 v190, v97, 0xba800000, v190
	v_fmamk_f32 v191, v97, 0xba800000, v191
	v_fmamk_f32 v192, v97, 0xba800000, v192
	v_fmamk_f32 v193, v97, 0xba800000, v193
	v_fmamk_f32 v194, v97, 0xba800000, v194
	v_fmamk_f32 v195, v97, 0xba800000, v195
	v_fmamk_f32 v196, v97, 0xba800000, v196
	v_fmamk_f32 v197, v97, 0xba800000, v197
	v_fmamk_f32 v198, v97, 0xba800000, v198
	v_fmamk_f32 v199, v97, 0xba800000, v199
	v_fmamk_f32 v200, v97, 0xba800000, v200
	v_fmamk_f32 v201, v97, 0xba800000, v201
	v_fmamk_f32 v202, v97, 0xba800000, v202
	v_fmamk_f32 v203, v97, 0xba800000, v203
	v_mul_f32_e32 v110, v140, v140
	v_mul_f32_e32 v111, v142, v142
	v_mul_f32_e32 v114, v156, v156
	v_mul_f32_e32 v115, v158, v158
	v_mul_f32_e32 v118, v172, v172
	v_mul_f32_e32 v119, v174, v174
	v_mul_f32_e32 v122, v188, v188
	v_mul_f32_e32 v123, v190, v190
	v_fmac_f32_e32 v110, v141, v141
	v_fmac_f32_e32 v111, v143, v143
	v_fmac_f32_e32 v114, v157, v157
	v_fmac_f32_e32 v115, v159, v159
	v_fmac_f32_e32 v118, v173, v173
	v_fmac_f32_e32 v119, v175, v175
	v_fmac_f32_e32 v122, v189, v189
	v_fmac_f32_e32 v123, v191, v191
	v_add_f32_e32 v110, v110, v111
	v_add_f32_e32 v114, v114, v115
	v_add_f32_e32 v118, v118, v119
	v_add_f32_e32 v122, v122, v123
	v_mov_b32_e32 v102, v110
	v_mov_b32_e32 v103, v114
	v_mov_b32_e32 v104, v118
	v_mov_b32_e32 v105, v122
	v_mul_f32_e32 v110, v144, v144
	v_mul_f32_e32 v111, v146, v146
	v_mul_f32_e32 v114, v160, v160
	v_mul_f32_e32 v115, v162, v162
	v_mul_f32_e32 v118, v176, v176
	v_mul_f32_e32 v119, v178, v178
	v_mul_f32_e32 v122, v192, v192
	v_mul_f32_e32 v123, v194, v194
	v_fmac_f32_e32 v110, v145, v145
	v_fmac_f32_e32 v111, v147, v147
	v_fmac_f32_e32 v114, v161, v161
	v_fmac_f32_e32 v115, v163, v163
	v_fmac_f32_e32 v118, v177, v177
	v_fmac_f32_e32 v119, v179, v179
	v_fmac_f32_e32 v122, v193, v193
	v_fmac_f32_e32 v123, v195, v195
	v_add_f32_e32 v110, v110, v111
	v_add_f32_e32 v114, v114, v115
	v_add_f32_e32 v118, v118, v119
	v_add_f32_e32 v122, v122, v123
	v_add_f32_e32 v102, v102, v110
	v_add_f32_e32 v103, v103, v114
	v_add_f32_e32 v104, v104, v118
	v_add_f32_e32 v105, v105, v122
	v_mul_f32_e32 v110, v148, v148
	v_mul_f32_e32 v111, v150, v150
	v_mul_f32_e32 v114, v164, v164
	v_mul_f32_e32 v115, v166, v166
	v_mul_f32_e32 v118, v180, v180
	v_mul_f32_e32 v119, v182, v182
	v_mul_f32_e32 v122, v196, v196
	v_mul_f32_e32 v123, v198, v198
	v_fmac_f32_e32 v110, v149, v149
	v_fmac_f32_e32 v111, v151, v151
	v_fmac_f32_e32 v114, v165, v165
	v_fmac_f32_e32 v115, v167, v167
	v_fmac_f32_e32 v118, v181, v181
	v_fmac_f32_e32 v119, v183, v183
	v_fmac_f32_e32 v122, v197, v197
	v_fmac_f32_e32 v123, v199, v199
	v_add_f32_e32 v110, v110, v111
	v_add_f32_e32 v114, v114, v115
	v_add_f32_e32 v118, v118, v119
	v_add_f32_e32 v122, v122, v123
	v_add_f32_e32 v102, v102, v110
	v_add_f32_e32 v103, v103, v114
; __device__ __forceinline__ float sigmoidf_(float x) { return fast_rcp(1.0f + fast_exp2(-1.4426950408889634f * x)); }
; #define KIN(i) (*(const float* const __attribute__((address_space(4)))*)(kp + kz + 8 * (i)))
; __global__ void __launch_bounds__(NTHR, 2) fwd_megakernel(Args args) {
;     ...
;                 for (int j = 0; j < 4; ++j) { x[j] = x[j] - mean; q += (x[j][0] * x[j][0] + x[j][1] * x[j][1]) + (x[j][2] * x[j][2] + x[j][3] * x[j][3]); }
;                 const float rstd = rsqrtf(wave_sum(q) * (1.0f / CCH) + LN_EPS); float z2 = 0.f;
; #pragma unroll
;                 for (int j = 0; j < 4; ++j) { const f32x4 gg = *(const f32x4*)(KIN(I_CONV_LN_G) + j * 256 + 4 * lane), bb = *(const f32x4*)(KIN(I_CONV_LN_B) + j * 256 + 4 * lane);
;                     f32x4 y = x[j] * rstd * gg + bb;
; #pragma unroll
;                     for (int e = 0; e < 4; ++e) { y[e] = y[e] * sigmoidf_(y[e]); z2 += y[e] * y[e]; }
	v_add_f32_e32 v104, v104, v118
	v_add_f32_e32 v105, v105, v122
	v_mul_f32_e32 v110, v152, v152
	v_mul_f32_e32 v111, v154, v154
	v_mul_f32_e32 v114, v168, v168
	v_mul_f32_e32 v115, v170, v170
	v_mul_f32_e32 v118, v184, v184
	v_mul_f32_e32 v119, v186, v186
	v_mul_f32_e32 v122, v200, v200
	v_mul_f32_e32 v123, v202, v202
	v_fmac_f32_e32 v110, v153, v153
	v_fmac_f32_e32 v111, v155, v155
	v_fmac_f32_e32 v114, v169, v169
	v_fmac_f32_e32 v115, v171, v171
	v_fmac_f32_e32 v118, v185, v185
	v_fmac_f32_e32 v119, v187, v187
	v_fmac_f32_e32 v122, v201, v201
	v_fmac_f32_e32 v123, v203, v203
	v_add_f32_e32 v110, v110, v111
	v_add_f32_e32 v114, v114, v115
	v_add_f32_e32 v118, v118, v119
	v_add_f32_e32 v122, v122, v123
	v_add_f32_e32 v102, v102, v110
	v_add_f32_e32 v103, v103, v114
	v_add_f32_e32 v104, v104, v118
	v_add_f32_e32 v105, v105, v122
	s_nop 1
	v_add_f32_dpp v98, v102, v102 quad_perm:[1,0,3,2] row_mask:0xf bank_mask:0xf
	v_add_f32_dpp v99, v103, v103 quad_perm:[1,0,3,2] row_mask:0xf bank_mask:0xf
	v_add_f32_dpp v100, v104, v104 quad_perm:[1,0,3,2] row_mask:0xf bank_mask:0xf
	v_add_f32_dpp v101, v105, v105 quad_perm:[1,0,3,2] row_mask:0xf bank_mask:0xf
	v_mov_b32_e32 v102, v98
	v_mov_b32_e32 v103, v99
	v_mov_b32_e32 v104, v100
	v_mov_b32_e32 v105, v101
	s_nop 1
	v_add_f32_dpp v98, v102, v102 quad_perm:[2,3,0,1] row_mask:0xf bank_mask:0xf
	v_add_f32_dpp v99, v103, v103 quad_perm:[2,3,0,1] row_mask:0xf bank_mask:0xf
	v_add_f32_dpp v100, v104, v104 quad_perm:[2,3,0,1] row_mask:0xf bank_mask:0xf
	v_add_f32_dpp v101, v105, v105 quad_perm:[2,3,0,1] row_mask:0xf bank_mask:0xf
	v_mov_b32_e32 v102, v98
	v_mov_b32_e32 v103, v99
	v_mov_b32_e32 v104, v100
	v_mov_b32_e32 v105, v101
	s_nop 1
	v_add_f32_dpp v98, v102, v102 row_half_mirror row_mask:0xf bank_mask:0xf
	v_add_f32_dpp v99, v103, v103 row_half_mirror row_mask:0xf bank_mask:0xf
	v_add_f32_dpp v100, v104, v104 row_half_mirror row_mask:0xf bank_mask:0xf
	v_add_f32_dpp v101, v105, v105 row_half_mirror row_mask:0xf bank_mask:0xf
	v_mov_b32_e32 v102, v98
	v_mov_b32_e32 v103, v99
	v_mov_b32_e32 v104, v100
	v_mov_b32_e32 v105, v101
	s_nop 1
	v_add_f32_dpp v98, v102, v102 row_mirror row_mask:0xf bank_mask:0xf
	v_add_f32_dpp v99, v103, v103 row_mirror row_mask:0xf bank_mask:0xf
	v_add_f32_dpp v100, v104, v104 row_mirror row_mask:0xf bank_mask:0xf
	v_add_f32_dpp v101, v105, v105 row_mirror row_mask:0xf bank_mask:0xf
	v_mov_b32_e32 v102, v98
	v_mov_b32_e32 v103, v99
	v_mov_b32_e32 v104, v100
	v_mov_b32_e32 v105, v101
	v_mov_b32_e32 v98, v102
	v_mov_b32_e32 v99, v103
	v_mov_b32_e32 v100, v104
	v_mov_b32_e32 v101, v105
	s_nop 1
	v_permlane16_swap_b32_e32 v102, v98
	v_permlane16_swap_b32_e32 v103, v99
	v_permlane16_swap_b32_e32 v104, v100
	v_permlane16_swap_b32_e32 v105, v101
	s_nop 1
	v_add_f32_e32 v102, v102, v98
	v_add_f32_e32 v103, v103, v99
	v_add_f32_e32 v104, v104, v100
	v_add_f32_e32 v105, v105, v101
	v_mov_b32_e32 v98, v102
	v_mov_b32_e32 v99, v103
	v_mov_b32_e32 v100, v104
	v_mov_b32_e32 v101, v105
	s_nop 1
	v_permlane32_swap_b32_e32 v102, v98
	v_permlane32_swap_b32_e32 v103, v99
	v_permlane32_swap_b32_e32 v104, v100
	v_permlane32_swap_b32_e32 v105, v101
	s_nop 1
	v_add_f32_e32 v102, v102, v98
	v_add_f32_e32 v103, v103, v99
	v_add_f32_e32 v104, v104, v100
	v_add_f32_e32 v105, v105, v101
	v_fmamk_f32 v106, v102, 0x3a800000, v226
	v_fmamk_f32 v107, v103, 0x3a800000, v226
	v_fmamk_f32 v108, v104, 0x3a800000, v226
	v_fmamk_f32 v109, v105, 0x3a800000, v226
	v_rsq_f32_e32 v106, v106
	v_rsq_f32_e32 v107, v107
	v_rsq_f32_e32 v108, v108
	v_rsq_f32_e32 v109, v109
	s_waitcnt vmcnt(0)
	v_mov_b32_e32 v102, 0
	v_mov_b32_e32 v103, 0
	v_mov_b32_e32 v104, 0
	v_mov_b32_e32 v105, 0
	v_mul_f32_e32 v140, v140, v106
	v_mul_f32_e32 v141, v141, v106
	v_mul_f32_e32 v142, v142, v106
	v_mul_f32_e32 v143, v143, v106
	v_mul_f32_e32 v156, v156, v107
	v_mul_f32_e32 v157, v157, v107
	v_mul_f32_e32 v158, v158, v107
	v_mul_f32_e32 v159, v159, v107
	v_mul_f32_e32 v172, v172, v108
	v_mul_f32_e32 v173, v173, v108
	v_mul_f32_e32 v174, v174, v108
	v_mul_f32_e32 v175, v175, v108
	v_mul_f32_e32 v188, v188, v109
	v_mul_f32_e32 v189, v189, v109
	v_mul_f32_e32 v190, v190, v109
	v_mul_f32_e32 v191, v191, v109
	v_fma_f32 v140, v140, v204, v232
	v_fma_f32 v141, v141, v205, v233
	v_fma_f32 v142, v142, v206, v234
	v_fma_f32 v143, v143, v207, v235
	v_fma_f32 v156, v156, v204, v232
	v_fma_f32 v157, v157, v205, v233
	v_fma_f32 v158, v158, v206, v234
	v_fma_f32 v159, v159, v207, v235
	v_fma_f32 v172, v172, v204, v232
	v_fma_f32 v173, v173, v205, v233
	v_fma_f32 v174, v174, v206, v234
	v_fma_f32 v175, v175, v207, v235
	v_fma_f32 v188, v188, v204, v232
	v_fma_f32 v189, v189, v205, v233
	v_fma_f32 v190, v190, v206, v234
	v_fma_f32 v191, v191, v207, v235
	v_mul_f32_e32 v110, 0xbfb8aa3b, v140
	v_mul_f32_e32 v111, 0xbfb8aa3b, v141
	v_mul_f32_e32 v112, 0xbfb8aa3b, v142
	v_mul_f32_e32 v113, 0xbfb8aa3b, v143
	v_mul_f32_e32 v114, 0xbfb8aa3b, v156
	v_mul_f32_e32 v115, 0xbfb8aa3b, v157
	v_mul_f32_e32 v116, 0xbfb8aa3b, v158
	v_mul_f32_e32 v117, 0xbfb8aa3b, v159
	v_mul_f32_e32 v118, 0xbfb8aa3b, v172
	v_mul_f32_e32 v119, 0xbfb8aa3b, v173
	v_mul_f32_e32 v120, 0xbfb8aa3b, v174
	v_mul_f32_e32 v121, 0xbfb8aa3b, v175
	v_mul_f32_e32 v122, 0xbfb8aa3b, v188
	v_mul_f32_e32 v123, 0xbfb8aa3b, v189
	v_mul_f32_e32 v124, 0xbfb8aa3b, v190
	v_mul_f32_e32 v125, 0xbfb8aa3b, v191
	v_exp_f32_e32 v110, v110
	v_exp_f32_e32 v111, v111
	v_exp_f32_e32 v112, v112
	v_exp_f32_e32 v113, v113
	v_exp_f32_e32 v114, v114
	v_exp_f32_e32 v115, v115
	v_exp_f32_e32 v116, v116
	v_exp_f32_e32 v117, v117
	v_exp_f32_e32 v118, v118
	v_exp_f32_e32 v119, v119
	v_exp_f32_e32 v120, v120
	v_exp_f32_e32 v121, v121
; __device__ __forceinline__ float sigmoidf_(float x) { return fast_rcp(1.0f + fast_exp2(-1.4426950408889634f * x)); }
; #define KIN(i) (*(const float* const __attribute__((address_space(4)))*)(kp + kz + 8 * (i)))
; __global__ void __launch_bounds__(NTHR, 2) fwd_megakernel(Args args) {
;     ...
;                 for (int j = 0; j < 4; ++j) { const f32x4 gg = *(const f32x4*)(KIN(I_CONV_LN_G) + j * 256 + 4 * lane), bb = *(const f32x4*)(KIN(I_CONV_LN_B) + j * 256 + 4 * lane);
;                     f32x4 y = x[j] * rstd * gg + bb;
; #pragma unroll
;                     for (int e = 0; e < 4; ++e) { y[e] = y[e] * sigmoidf_(y[e]); z2 += y[e] * y[e]; }
;                     x[j] = y; }
	v_exp_f32_e32 v122, v122
	v_exp_f32_e32 v123, v123
	v_exp_f32_e32 v124, v124
	v_exp_f32_e32 v125, v125
	v_add_f32_e32 v110, 1.0, v110
	v_add_f32_e32 v111, 1.0, v111
	v_add_f32_e32 v112, 1.0, v112
	v_add_f32_e32 v113, 1.0, v113
	v_add_f32_e32 v114, 1.0, v114
	v_add_f32_e32 v115, 1.0, v115
	v_add_f32_e32 v116, 1.0, v116
	v_add_f32_e32 v117, 1.0, v117
	v_add_f32_e32 v118, 1.0, v118
	v_add_f32_e32 v119, 1.0, v119
	v_add_f32_e32 v120, 1.0, v120
	v_add_f32_e32 v121, 1.0, v121
	v_add_f32_e32 v122, 1.0, v122
	v_add_f32_e32 v123, 1.0, v123
	v_add_f32_e32 v124, 1.0, v124
	v_add_f32_e32 v125, 1.0, v125
	v_rcp_f32_e32 v110, v110
	v_rcp_f32_e32 v111, v111
	v_rcp_f32_e32 v112, v112
	v_rcp_f32_e32 v113, v113
	v_rcp_f32_e32 v114, v114
	v_rcp_f32_e32 v115, v115
	v_rcp_f32_e32 v116, v116
	v_rcp_f32_e32 v117, v117
	v_rcp_f32_e32 v118, v118
	v_rcp_f32_e32 v119, v119
	v_rcp_f32_e32 v120, v120
	v_rcp_f32_e32 v121, v121
	v_rcp_f32_e32 v122, v122
	v_rcp_f32_e32 v123, v123
	v_rcp_f32_e32 v124, v124
	v_rcp_f32_e32 v125, v125
	v_mul_f32_e32 v140, v140, v110
	v_mul_f32_e32 v141, v141, v111
	v_mul_f32_e32 v142, v142, v112
	v_mul_f32_e32 v143, v143, v113
	v_mul_f32_e32 v156, v156, v114
	v_mul_f32_e32 v157, v157, v115
	v_mul_f32_e32 v158, v158, v116
	v_mul_f32_e32 v159, v159, v117
	v_mul_f32_e32 v172, v172, v118
	v_mul_f32_e32 v173, v173, v119
	v_mul_f32_e32 v174, v174, v120
	v_mul_f32_e32 v175, v175, v121
	v_mul_f32_e32 v188, v188, v122
	v_mul_f32_e32 v189, v189, v123
	v_mul_f32_e32 v190, v190, v124
	v_mul_f32_e32 v191, v191, v125
	v_fmac_f32_e32 v102, v140, v140
	v_fmac_f32_e32 v103, v156, v156
	v_fmac_f32_e32 v104, v172, v172
	v_fmac_f32_e32 v105, v188, v188
	v_fmac_f32_e32 v102, v141, v141
	v_fmac_f32_e32 v103, v157, v157
	v_fmac_f32_e32 v104, v173, v173
	v_fmac_f32_e32 v105, v189, v189
	v_fmac_f32_e32 v102, v142, v142
	v_fmac_f32_e32 v103, v158, v158
	v_fmac_f32_e32 v104, v174, v174
	v_fmac_f32_e32 v105, v190, v190
	v_fmac_f32_e32 v102, v143, v143
	v_fmac_f32_e32 v103, v159, v159
	v_fmac_f32_e32 v104, v175, v175
	v_fmac_f32_e32 v105, v191, v191
	v_mul_f32_e32 v144, v144, v106
	v_mul_f32_e32 v145, v145, v106
	v_mul_f32_e32 v146, v146, v106
	v_mul_f32_e32 v147, v147, v106
	v_mul_f32_e32 v160, v160, v107
	v_mul_f32_e32 v161, v161, v107
	v_mul_f32_e32 v162, v162, v107
	v_mul_f32_e32 v163, v163, v107
	v_mul_f32_e32 v176, v176, v108
	v_mul_f32_e32 v177, v177, v108
	v_mul_f32_e32 v178, v178, v108
	v_mul_f32_e32 v179, v179, v108
	v_mul_f32_e32 v192, v192, v109
	v_mul_f32_e32 v193, v193, v109
	v_mul_f32_e32 v194, v194, v109
	v_mul_f32_e32 v195, v195, v109
	v_fma_f32 v144, v144, v208, v236
	v_fma_f32 v145, v145, v209, v237
	v_fma_f32 v146, v146, v210, v238
	v_fma_f32 v147, v147, v211, v239
	v_fma_f32 v160, v160, v208, v236
	v_fma_f32 v161, v161, v209, v237
	v_fma_f32 v162, v162, v210, v238
	v_fma_f32 v163, v163, v211, v239
	v_fma_f32 v176, v176, v208, v236
	v_fma_f32 v177, v177, v209, v237
	v_fma_f32 v178, v178, v210, v238
	v_fma_f32 v179, v179, v211, v239
	v_fma_f32 v192, v192, v208, v236
	v_fma_f32 v193, v193, v209, v237
	v_fma_f32 v194, v194, v210, v238
	v_fma_f32 v195, v195, v211, v239
	v_mul_f32_e32 v110, 0xbfb8aa3b, v144
	v_mul_f32_e32 v111, 0xbfb8aa3b, v145
	v_mul_f32_e32 v112, 0xbfb8aa3b, v146
	v_mul_f32_e32 v113, 0xbfb8aa3b, v147
	v_mul_f32_e32 v114, 0xbfb8aa3b, v160
	v_mul_f32_e32 v115, 0xbfb8aa3b, v161
	v_mul_f32_e32 v116, 0xbfb8aa3b, v162
	v_mul_f32_e32 v117, 0xbfb8aa3b, v163
	v_mul_f32_e32 v118, 0xbfb8aa3b, v176
	v_mul_f32_e32 v119, 0xbfb8aa3b, v177
	v_mul_f32_e32 v120, 0xbfb8aa3b, v178
	v_mul_f32_e32 v121, 0xbfb8aa3b, v179
	v_mul_f32_e32 v122, 0xbfb8aa3b, v192
	v_mul_f32_e32 v123, 0xbfb8aa3b, v193
	v_mul_f32_e32 v124, 0xbfb8aa3b, v194
	v_mul_f32_e32 v125, 0xbfb8aa3b, v195
	v_exp_f32_e32 v110, v110
	v_exp_f32_e32 v111, v111
	v_exp_f32_e32 v112, v112
	v_exp_f32_e32 v113, v113
	v_exp_f32_e32 v114, v114
	v_exp_f32_e32 v115, v115
	v_exp_f32_e32 v116, v116
	v_exp_f32_e32 v117, v117
	v_exp_f32_e32 v118, v118
	v_exp_f32_e32 v119, v119
	v_exp_f32_e32 v120, v120
	v_exp_f32_e32 v121, v121
	v_exp_f32_e32 v122, v122
	v_exp_f32_e32 v123, v123
	v_exp_f32_e32 v124, v124
	v_exp_f32_e32 v125, v125
	v_add_f32_e32 v110, 1.0, v110
	v_add_f32_e32 v111, 1.0, v111
	v_add_f32_e32 v112, 1.0, v112
	v_add_f32_e32 v113, 1.0, v113
	v_add_f32_e32 v114, 1.0, v114
	v_add_f32_e32 v115, 1.0, v115
	v_add_f32_e32 v116, 1.0, v116
	v_add_f32_e32 v117, 1.0, v117
	v_add_f32_e32 v118, 1.0, v118
	v_add_f32_e32 v119, 1.0, v119
	v_add_f32_e32 v120, 1.0, v120
	v_add_f32_e32 v121, 1.0, v121
	v_add_f32_e32 v122, 1.0, v122
	v_add_f32_e32 v123, 1.0, v123
	v_add_f32_e32 v124, 1.0, v124
	v_add_f32_e32 v125, 1.0, v125
	v_rcp_f32_e32 v110, v110
	v_rcp_f32_e32 v111, v111
	v_rcp_f32_e32 v112, v112
	v_rcp_f32_e32 v113, v113
	v_rcp_f32_e32 v114, v114
	v_rcp_f32_e32 v115, v115
	v_rcp_f32_e32 v116, v116
	v_rcp_f32_e32 v117, v117
	v_rcp_f32_e32 v118, v118
	v_rcp_f32_e32 v119, v119
	v_rcp_f32_e32 v120, v120
	v_rcp_f32_e32 v121, v121
	v_rcp_f32_e32 v122, v122
	v_rcp_f32_e32 v123, v123
	v_rcp_f32_e32 v124, v124
	v_rcp_f32_e32 v125, v125
	v_mul_f32_e32 v144, v144, v110
	v_mul_f32_e32 v145, v145, v111
	v_mul_f32_e32 v146, v146, v112
	v_mul_f32_e32 v147, v147, v113
	v_mul_f32_e32 v160, v160, v114
	v_mul_f32_e32 v161, v161, v115
	v_mul_f32_e32 v162, v162, v116
	v_mul_f32_e32 v163, v163, v117
	v_mul_f32_e32 v176, v176, v118
	v_mul_f32_e32 v177, v177, v119
	v_mul_f32_e32 v178, v178, v120
	v_mul_f32_e32 v179, v179, v121
	v_mul_f32_e32 v192, v192, v122
	v_mul_f32_e32 v193, v193, v123
	v_mul_f32_e32 v194, v194, v124
	v_mul_f32_e32 v195, v195, v125
	v_fmac_f32_e32 v102, v144, v144
	v_fmac_f32_e32 v103, v160, v160
; __device__ __forceinline__ float sigmoidf_(float x) { return fast_rcp(1.0f + fast_exp2(-1.4426950408889634f * x)); }
; #define KIN(i) (*(const float* const __attribute__((address_space(4)))*)(kp + kz + 8 * (i)))
; __global__ void __launch_bounds__(NTHR, 2) fwd_megakernel(Args args) {
;     ...
;                 for (int j = 0; j < 4; ++j) { const f32x4 gg = *(const f32x4*)(KIN(I_CONV_LN_G) + j * 256 + 4 * lane), bb = *(const f32x4*)(KIN(I_CONV_LN_B) + j * 256 + 4 * lane);
;                     f32x4 y = x[j] * rstd * gg + bb;
; #pragma unroll
;                     for (int e = 0; e < 4; ++e) { y[e] = y[e] * sigmoidf_(y[e]); z2 += y[e] * y[e]; }
;                     x[j] = y; }
	v_fmac_f32_e32 v104, v176, v176
	v_fmac_f32_e32 v105, v192, v192
	v_fmac_f32_e32 v102, v145, v145
	v_fmac_f32_e32 v103, v161, v161
	v_fmac_f32_e32 v104, v177, v177
	v_fmac_f32_e32 v105, v193, v193
	v_fmac_f32_e32 v102, v146, v146
	v_fmac_f32_e32 v103, v162, v162
	v_fmac_f32_e32 v104, v178, v178
	v_fmac_f32_e32 v105, v194, v194
	v_fmac_f32_e32 v102, v147, v147
	v_fmac_f32_e32 v103, v163, v163
	v_fmac_f32_e32 v104, v179, v179
	v_fmac_f32_e32 v105, v195, v195
	v_mul_f32_e32 v148, v148, v106
	v_mul_f32_e32 v149, v149, v106
	v_mul_f32_e32 v150, v150, v106
	v_mul_f32_e32 v151, v151, v106
	v_mul_f32_e32 v164, v164, v107
	v_mul_f32_e32 v165, v165, v107
	v_mul_f32_e32 v166, v166, v107
	v_mul_f32_e32 v167, v167, v107
	v_mul_f32_e32 v180, v180, v108
	v_mul_f32_e32 v181, v181, v108
	v_mul_f32_e32 v182, v182, v108
	v_mul_f32_e32 v183, v183, v108
	v_mul_f32_e32 v196, v196, v109
	v_mul_f32_e32 v197, v197, v109
	v_mul_f32_e32 v198, v198, v109
	v_mul_f32_e32 v199, v199, v109
	v_fma_f32 v148, v148, v212, v240
	v_fma_f32 v149, v149, v213, v241
	v_fma_f32 v150, v150, v214, v242
	v_fma_f32 v151, v151, v215, v243
	v_fma_f32 v164, v164, v212, v240
	v_fma_f32 v165, v165, v213, v241
	v_fma_f32 v166, v166, v214, v242
	v_fma_f32 v167, v167, v215, v243
	v_fma_f32 v180, v180, v212, v240
	v_fma_f32 v181, v181, v213, v241
	v_fma_f32 v182, v182, v214, v242
	v_fma_f32 v183, v183, v215, v243
	v_fma_f32 v196, v196, v212, v240
	v_fma_f32 v197, v197, v213, v241
	v_fma_f32 v198, v198, v214, v242
	v_fma_f32 v199, v199, v215, v243
	v_mul_f32_e32 v110, 0xbfb8aa3b, v148
	v_mul_f32_e32 v111, 0xbfb8aa3b, v149
	v_mul_f32_e32 v112, 0xbfb8aa3b, v150
	v_mul_f32_e32 v113, 0xbfb8aa3b, v151
	v_mul_f32_e32 v114, 0xbfb8aa3b, v164
	v_mul_f32_e32 v115, 0xbfb8aa3b, v165
	v_mul_f32_e32 v116, 0xbfb8aa3b, v166
	v_mul_f32_e32 v117, 0xbfb8aa3b, v167
	v_mul_f32_e32 v118, 0xbfb8aa3b, v180
	v_mul_f32_e32 v119, 0xbfb8aa3b, v181
	v_mul_f32_e32 v120, 0xbfb8aa3b, v182
	v_mul_f32_e32 v121, 0xbfb8aa3b, v183
	v_mul_f32_e32 v122, 0xbfb8aa3b, v196
	v_mul_f32_e32 v123, 0xbfb8aa3b, v197
	v_mul_f32_e32 v124, 0xbfb8aa3b, v198
	v_mul_f32_e32 v125, 0xbfb8aa3b, v199
	v_exp_f32_e32 v110, v110
	v_exp_f32_e32 v111, v111
	v_exp_f32_e32 v112, v112
	v_exp_f32_e32 v113, v113
	v_exp_f32_e32 v114, v114
	v_exp_f32_e32 v115, v115
	v_exp_f32_e32 v116, v116
	v_exp_f32_e32 v117, v117
	v_exp_f32_e32 v118, v118
	v_exp_f32_e32 v119, v119
	v_exp_f32_e32 v120, v120
	v_exp_f32_e32 v121, v121
	v_exp_f32_e32 v122, v122
	v_exp_f32_e32 v123, v123
	v_exp_f32_e32 v124, v124
	v_exp_f32_e32 v125, v125
	v_add_f32_e32 v110, 1.0, v110
	v_add_f32_e32 v111, 1.0, v111
	v_add_f32_e32 v112, 1.0, v112
	v_add_f32_e32 v113, 1.0, v113
	v_add_f32_e32 v114, 1.0, v114
	v_add_f32_e32 v115, 1.0, v115
	v_add_f32_e32 v116, 1.0, v116
	v_add_f32_e32 v117, 1.0, v117
	v_add_f32_e32 v118, 1.0, v118
	v_add_f32_e32 v119, 1.0, v119
	v_add_f32_e32 v120, 1.0, v120
	v_add_f32_e32 v121, 1.0, v121
	v_add_f32_e32 v122, 1.0, v122
	v_add_f32_e32 v123, 1.0, v123
	v_add_f32_e32 v124, 1.0, v124
	v_add_f32_e32 v125, 1.0, v125
	v_rcp_f32_e32 v110, v110
	v_rcp_f32_e32 v111, v111
	v_rcp_f32_e32 v112, v112
	v_rcp_f32_e32 v113, v113
	v_rcp_f32_e32 v114, v114
	v_rcp_f32_e32 v115, v115
	v_rcp_f32_e32 v116, v116
	v_rcp_f32_e32 v117, v117
	v_rcp_f32_e32 v118, v118
	v_rcp_f32_e32 v119, v119
	v_rcp_f32_e32 v120, v120
	v_rcp_f32_e32 v121, v121
	v_rcp_f32_e32 v122, v122
	v_rcp_f32_e32 v123, v123
	v_rcp_f32_e32 v124, v124
	v_rcp_f32_e32 v125, v125
	v_mul_f32_e32 v148, v148, v110
	v_mul_f32_e32 v149, v149, v111
	v_mul_f32_e32 v150, v150, v112
	v_mul_f32_e32 v151, v151, v113
	v_mul_f32_e32 v164, v164, v114
	v_mul_f32_e32 v165, v165, v115
	v_mul_f32_e32 v166, v166, v116
	v_mul_f32_e32 v167, v167, v117
	v_mul_f32_e32 v180, v180, v118
	v_mul_f32_e32 v181, v181, v119
	v_mul_f32_e32 v182, v182, v120
	v_mul_f32_e32 v183, v183, v121
	v_mul_f32_e32 v196, v196, v122
	v_mul_f32_e32 v197, v197, v123
	v_mul_f32_e32 v198, v198, v124
	v_mul_f32_e32 v199, v199, v125
	v_fmac_f32_e32 v102, v148, v148
	v_fmac_f32_e32 v103, v164, v164
	v_fmac_f32_e32 v104, v180, v180
	v_fmac_f32_e32 v105, v196, v196
	v_fmac_f32_e32 v102, v149, v149
	v_fmac_f32_e32 v103, v165, v165
	v_fmac_f32_e32 v104, v181, v181
	v_fmac_f32_e32 v105, v197, v197
	v_fmac_f32_e32 v102, v150, v150
	v_fmac_f32_e32 v103, v166, v166
	v_fmac_f32_e32 v104, v182, v182
	v_fmac_f32_e32 v105, v198, v198
	v_fmac_f32_e32 v102, v151, v151
	v_fmac_f32_e32 v103, v167, v167
	v_fmac_f32_e32 v104, v183, v183
	v_fmac_f32_e32 v105, v199, v199
	v_mul_f32_e32 v152, v152, v106
	v_mul_f32_e32 v153, v153, v106
	v_mul_f32_e32 v154, v154, v106
	v_mul_f32_e32 v155, v155, v106
	v_mul_f32_e32 v168, v168, v107
	v_mul_f32_e32 v169, v169, v107
	v_mul_f32_e32 v170, v170, v107
	v_mul_f32_e32 v171, v171, v107
	v_mul_f32_e32 v184, v184, v108
	v_mul_f32_e32 v185, v185, v108
	v_mul_f32_e32 v186, v186, v108
	v_mul_f32_e32 v187, v187, v108
	v_mul_f32_e32 v200, v200, v109
	v_mul_f32_e32 v201, v201, v109
	v_mul_f32_e32 v202, v202, v109
	v_mul_f32_e32 v203, v203, v109
	v_fma_f32 v152, v152, v228, v0
	v_fma_f32 v153, v153, v229, v1
	v_fma_f32 v154, v154, v230, v2
	v_fma_f32 v155, v155, v231, v3
	v_fma_f32 v168, v168, v228, v0
	v_fma_f32 v169, v169, v229, v1
	v_fma_f32 v170, v170, v230, v2
	v_fma_f32 v171, v171, v231, v3
	v_fma_f32 v184, v184, v228, v0
	v_fma_f32 v185, v185, v229, v1
	v_fma_f32 v186, v186, v230, v2
	v_fma_f32 v187, v187, v231, v3
	v_fma_f32 v200, v200, v228, v0
	v_fma_f32 v201, v201, v229, v1
	v_fma_f32 v202, v202, v230, v2
	v_fma_f32 v203, v203, v231, v3
	v_mul_f32_e32 v110, 0xbfb8aa3b, v152
	v_mul_f32_e32 v111, 0xbfb8aa3b, v153
	v_mul_f32_e32 v112, 0xbfb8aa3b, v154
; __device__ __forceinline__ float sigmoidf_(float x) { return fast_rcp(1.0f + fast_exp2(-1.4426950408889634f * x)); }
; __global__ void __launch_bounds__(NTHR, 2) fwd_megakernel(Args args) {
;     ...
;                     for (int e = 0; e < 4; ++e) { y[e] = y[e] * sigmoidf_(y[e]); z2 += y[e] * y[e]; }
;                     x[j] = y; }
;                 const float r2 = rsqrtf(wave_sum(z2) * (1.0f / CCH) + RMS_EPS);
	v_mul_f32_e32 v113, 0xbfb8aa3b, v155
	v_mul_f32_e32 v114, 0xbfb8aa3b, v168
	v_mul_f32_e32 v115, 0xbfb8aa3b, v169
	v_mul_f32_e32 v116, 0xbfb8aa3b, v170
	v_mul_f32_e32 v117, 0xbfb8aa3b, v171
	v_mul_f32_e32 v118, 0xbfb8aa3b, v184
	v_mul_f32_e32 v119, 0xbfb8aa3b, v185
	v_mul_f32_e32 v120, 0xbfb8aa3b, v186
	v_mul_f32_e32 v121, 0xbfb8aa3b, v187
	v_mul_f32_e32 v122, 0xbfb8aa3b, v200
	v_mul_f32_e32 v123, 0xbfb8aa3b, v201
	v_mul_f32_e32 v124, 0xbfb8aa3b, v202
	v_mul_f32_e32 v125, 0xbfb8aa3b, v203
	v_exp_f32_e32 v110, v110
	v_exp_f32_e32 v111, v111
	v_exp_f32_e32 v112, v112
	v_exp_f32_e32 v113, v113
	v_exp_f32_e32 v114, v114
	v_exp_f32_e32 v115, v115
	v_exp_f32_e32 v116, v116
	v_exp_f32_e32 v117, v117
	v_exp_f32_e32 v118, v118
	v_exp_f32_e32 v119, v119
	v_exp_f32_e32 v120, v120
	v_exp_f32_e32 v121, v121
	v_exp_f32_e32 v122, v122
	v_exp_f32_e32 v123, v123
	v_exp_f32_e32 v124, v124
	v_exp_f32_e32 v125, v125
	v_add_f32_e32 v110, 1.0, v110
	v_add_f32_e32 v111, 1.0, v111
	v_add_f32_e32 v112, 1.0, v112
	v_add_f32_e32 v113, 1.0, v113
	v_add_f32_e32 v114, 1.0, v114
	v_add_f32_e32 v115, 1.0, v115
	v_add_f32_e32 v116, 1.0, v116
	v_add_f32_e32 v117, 1.0, v117
	v_add_f32_e32 v118, 1.0, v118
	v_add_f32_e32 v119, 1.0, v119
	v_add_f32_e32 v120, 1.0, v120
	v_add_f32_e32 v121, 1.0, v121
	v_add_f32_e32 v122, 1.0, v122
	v_add_f32_e32 v123, 1.0, v123
	v_add_f32_e32 v124, 1.0, v124
	v_add_f32_e32 v125, 1.0, v125
	v_rcp_f32_e32 v110, v110
	v_rcp_f32_e32 v111, v111
	v_rcp_f32_e32 v112, v112
	v_rcp_f32_e32 v113, v113
	v_rcp_f32_e32 v114, v114
	v_rcp_f32_e32 v115, v115
	v_rcp_f32_e32 v116, v116
	v_rcp_f32_e32 v117, v117
	v_rcp_f32_e32 v118, v118
	v_rcp_f32_e32 v119, v119
	v_rcp_f32_e32 v120, v120
	v_rcp_f32_e32 v121, v121
	v_rcp_f32_e32 v122, v122
	v_rcp_f32_e32 v123, v123
	v_rcp_f32_e32 v124, v124
	v_rcp_f32_e32 v125, v125
	v_mul_f32_e32 v152, v152, v110
	v_mul_f32_e32 v153, v153, v111
	v_mul_f32_e32 v154, v154, v112
	v_mul_f32_e32 v155, v155, v113
	v_mul_f32_e32 v168, v168, v114
	v_mul_f32_e32 v169, v169, v115
	v_mul_f32_e32 v170, v170, v116
	v_mul_f32_e32 v171, v171, v117
	v_mul_f32_e32 v184, v184, v118
	v_mul_f32_e32 v185, v185, v119
	v_mul_f32_e32 v186, v186, v120
	v_mul_f32_e32 v187, v187, v121
	v_mul_f32_e32 v200, v200, v122
	v_mul_f32_e32 v201, v201, v123
	v_mul_f32_e32 v202, v202, v124
	v_mul_f32_e32 v203, v203, v125
	v_fmac_f32_e32 v102, v152, v152
	v_fmac_f32_e32 v103, v168, v168
	v_fmac_f32_e32 v104, v184, v184
	v_fmac_f32_e32 v105, v200, v200
	v_fmac_f32_e32 v102, v153, v153
	v_fmac_f32_e32 v103, v169, v169
	v_fmac_f32_e32 v104, v185, v185
	v_fmac_f32_e32 v105, v201, v201
	v_fmac_f32_e32 v102, v154, v154
	v_fmac_f32_e32 v103, v170, v170
	v_fmac_f32_e32 v104, v186, v186
	v_fmac_f32_e32 v105, v202, v202
	v_fmac_f32_e32 v102, v155, v155
	v_fmac_f32_e32 v103, v171, v171
	v_fmac_f32_e32 v104, v187, v187
	v_fmac_f32_e32 v105, v203, v203
	s_nop 1
	v_add_f32_dpp v98, v102, v102 quad_perm:[1,0,3,2] row_mask:0xf bank_mask:0xf
	v_add_f32_dpp v99, v103, v103 quad_perm:[1,0,3,2] row_mask:0xf bank_mask:0xf
	v_add_f32_dpp v100, v104, v104 quad_perm:[1,0,3,2] row_mask:0xf bank_mask:0xf
	v_add_f32_dpp v101, v105, v105 quad_perm:[1,0,3,2] row_mask:0xf bank_mask:0xf
	v_mov_b32_e32 v102, v98
	v_mov_b32_e32 v103, v99
	v_mov_b32_e32 v104, v100
	v_mov_b32_e32 v105, v101
	s_nop 1
	v_add_f32_dpp v98, v102, v102 quad_perm:[2,3,0,1] row_mask:0xf bank_mask:0xf
	v_add_f32_dpp v99, v103, v103 quad_perm:[2,3,0,1] row_mask:0xf bank_mask:0xf
	v_add_f32_dpp v100, v104, v104 quad_perm:[2,3,0,1] row_mask:0xf bank_mask:0xf
	v_add_f32_dpp v101, v105, v105 quad_perm:[2,3,0,1] row_mask:0xf bank_mask:0xf
	v_mov_b32_e32 v102, v98
	v_mov_b32_e32 v103, v99
	v_mov_b32_e32 v104, v100
	v_mov_b32_e32 v105, v101
	s_nop 1
	v_add_f32_dpp v98, v102, v102 row_half_mirror row_mask:0xf bank_mask:0xf
	v_add_f32_dpp v99, v103, v103 row_half_mirror row_mask:0xf bank_mask:0xf
	v_add_f32_dpp v100, v104, v104 row_half_mirror row_mask:0xf bank_mask:0xf
	v_add_f32_dpp v101, v105, v105 row_half_mirror row_mask:0xf bank_mask:0xf
	v_mov_b32_e32 v102, v98
	v_mov_b32_e32 v103, v99
	v_mov_b32_e32 v104, v100
	v_mov_b32_e32 v105, v101
	s_nop 1
	v_add_f32_dpp v98, v102, v102 row_mirror row_mask:0xf bank_mask:0xf
	v_add_f32_dpp v99, v103, v103 row_mirror row_mask:0xf bank_mask:0xf
	v_add_f32_dpp v100, v104, v104 row_mirror row_mask:0xf bank_mask:0xf
	v_add_f32_dpp v101, v105, v105 row_mirror row_mask:0xf bank_mask:0xf
	v_mov_b32_e32 v102, v98
	v_mov_b32_e32 v103, v99
	v_mov_b32_e32 v104, v100
	v_mov_b32_e32 v105, v101
	v_mov_b32_e32 v98, v102
	v_mov_b32_e32 v99, v103
	v_mov_b32_e32 v100, v104
	v_mov_b32_e32 v101, v105
	s_nop 1
	v_permlane16_swap_b32_e32 v102, v98
	v_permlane16_swap_b32_e32 v103, v99
	v_permlane16_swap_b32_e32 v104, v100
	v_permlane16_swap_b32_e32 v105, v101
	s_nop 1
	v_add_f32_e32 v102, v102, v98
	v_add_f32_e32 v103, v103, v99
	v_add_f32_e32 v104, v104, v100
	v_add_f32_e32 v105, v105, v101
	v_mov_b32_e32 v98, v102
	v_mov_b32_e32 v99, v103
	v_mov_b32_e32 v100, v104
	v_mov_b32_e32 v101, v105
	s_nop 1
	v_permlane32_swap_b32_e32 v102, v98
	v_permlane32_swap_b32_e32 v103, v99
	v_permlane32_swap_b32_e32 v104, v100
	v_permlane32_swap_b32_e32 v105, v101
	s_nop 1
	v_add_f32_e32 v102, v102, v98
	v_add_f32_e32 v103, v103, v99
	v_add_f32_e32 v104, v104, v100
	v_add_f32_e32 v105, v105, v101
	v_fmamk_f32 v106, v102, 0x3a800000, v227
	v_fmamk_f32 v107, v103, 0x3a800000, v227
	v_fmamk_f32 v108, v104, 0x3a800000, v227
	v_fmamk_f32 v109, v105, 0x3a800000, v227
	v_rsq_f32_e32 v106, v106
	v_rsq_f32_e32 v107, v107
	v_rsq_f32_e32 v108, v108
	v_rsq_f32_e32 v109, v109
	s_nop 0
	v_mul_f32_e32 v140, v140, v106
	v_mul_f32_e32 v141, v141, v106
; __device__ __forceinline__ unsigned cvt_pk_bf16(float lo, float hi) { unsigned r; asm volatile("v_cvt_pk_bf16_f32 %0, %1, %2" : "=v"(r) : "v"(lo), "v"(hi)); return r; }
; #define KIN(i) (*(const float* const __attribute__((address_space(4)))*)(kp + kz + 8 * (i)))
; __global__ void __launch_bounds__(NTHR, 2) fwd_megakernel(Args args) {
;     ...
;                 const float r2 = rsqrtf(wave_sum(z2) * (1.0f / CCH) + RMS_EPS);
; #pragma unroll
;                 for (int j = 0; j < 4; ++j) { const f32x4 gg = *(const f32x4*)(KIN(I_OUT_NORM_CONV) + j * 256 + 4 * lane); const f32x4 y = x[j] * r2 * gg;
;                     u32x2 w; w.x = cvt_pk_bf16(y[0], y[1]); w.y = cvt_pk_bf16(y[2], y[3]); *(u32x2*)(Y + (size_t)(t0 + r) * D + j * 256 + 4 * lane) = w; }
	v_mul_f32_e32 v142, v142, v106
	v_mul_f32_e32 v143, v143, v106
	v_mul_f32_e32 v156, v156, v107
	v_mul_f32_e32 v157, v157, v107
	v_mul_f32_e32 v158, v158, v107
	v_mul_f32_e32 v159, v159, v107
	v_mul_f32_e32 v172, v172, v108
	v_mul_f32_e32 v173, v173, v108
	v_mul_f32_e32 v174, v174, v108
	v_mul_f32_e32 v175, v175, v108
	v_mul_f32_e32 v188, v188, v109
	v_mul_f32_e32 v189, v189, v109
	v_mul_f32_e32 v190, v190, v109
	v_mul_f32_e32 v191, v191, v109
	v_mul_f32_e32 v140, v140, v4
	v_mul_f32_e32 v141, v141, v5
	v_mul_f32_e32 v142, v142, v6
	v_mul_f32_e32 v143, v143, v7
	v_mul_f32_e32 v156, v156, v4
	v_mul_f32_e32 v157, v157, v5
	v_mul_f32_e32 v158, v158, v6
	v_mul_f32_e32 v159, v159, v7
	v_mul_f32_e32 v172, v172, v4
	v_mul_f32_e32 v173, v173, v5
	v_mul_f32_e32 v174, v174, v6
	v_mul_f32_e32 v175, v175, v7
	v_mul_f32_e32 v188, v188, v4
	v_mul_f32_e32 v189, v189, v5
	v_mul_f32_e32 v190, v190, v6
	v_mul_f32_e32 v191, v191, v7
	v_cvt_pk_bf16_f32 v134, v140, v141
	v_cvt_pk_bf16_f32 v135, v142, v143
	v_cvt_pk_bf16_f32 v136, v156, v157
	v_cvt_pk_bf16_f32 v137, v158, v159
	v_cvt_pk_bf16_f32 v242, v172, v173
	v_cvt_pk_bf16_f32 v243, v174, v175
	v_cvt_pk_bf16_f32 v244, v188, v189
	v_cvt_pk_bf16_f32 v245, v190, v191
	global_store_dwordx2 v[126:127], v[134:135], off
	global_store_dwordx2 v[128:129], v[136:137], off
	global_store_dwordx2 v[130:131], v[242:243], off
	global_store_dwordx2 v[132:133], v[244:245], off
	s_nop 1
	v_mul_f32_e32 v144, v144, v106
	v_mul_f32_e32 v145, v145, v106
	v_mul_f32_e32 v146, v146, v106
	v_mul_f32_e32 v147, v147, v106
	v_mul_f32_e32 v160, v160, v107
	v_mul_f32_e32 v161, v161, v107
	v_mul_f32_e32 v162, v162, v107
	v_mul_f32_e32 v163, v163, v107
	v_mul_f32_e32 v176, v176, v108
	v_mul_f32_e32 v177, v177, v108
	v_mul_f32_e32 v178, v178, v108
	v_mul_f32_e32 v179, v179, v108
	v_mul_f32_e32 v192, v192, v109
	v_mul_f32_e32 v193, v193, v109
	v_mul_f32_e32 v194, v194, v109
	v_mul_f32_e32 v195, v195, v109
	v_mul_f32_e32 v144, v144, v8
	v_mul_f32_e32 v145, v145, v9
	v_mul_f32_e32 v146, v146, v10
	v_mul_f32_e32 v147, v147, v11
	v_mul_f32_e32 v160, v160, v8
	v_mul_f32_e32 v161, v161, v9
	v_mul_f32_e32 v162, v162, v10
	v_mul_f32_e32 v163, v163, v11
	v_mul_f32_e32 v176, v176, v8
	v_mul_f32_e32 v177, v177, v9
	v_mul_f32_e32 v178, v178, v10
	v_mul_f32_e32 v179, v179, v11
	v_mul_f32_e32 v192, v192, v8
	v_mul_f32_e32 v193, v193, v9
	v_mul_f32_e32 v194, v194, v10
	v_mul_f32_e32 v195, v195, v11
	v_cvt_pk_bf16_f32 v134, v144, v145
	v_cvt_pk_bf16_f32 v135, v146, v147
	v_cvt_pk_bf16_f32 v136, v160, v161
	v_cvt_pk_bf16_f32 v137, v162, v163
	v_cvt_pk_bf16_f32 v242, v176, v177
	v_cvt_pk_bf16_f32 v243, v178, v179
	v_cvt_pk_bf16_f32 v244, v192, v193
	v_cvt_pk_bf16_f32 v245, v194, v195
	global_store_dwordx2 v[126:127], v[134:135], off offset:512
	global_store_dwordx2 v[128:129], v[136:137], off offset:512
	global_store_dwordx2 v[130:131], v[242:243], off offset:512
	global_store_dwordx2 v[132:133], v[244:245], off offset:512
	s_nop 1
	v_mul_f32_e32 v148, v148, v106
	v_mul_f32_e32 v149, v149, v106
	v_mul_f32_e32 v150, v150, v106
	v_mul_f32_e32 v151, v151, v106
	v_mul_f32_e32 v164, v164, v107
	v_mul_f32_e32 v165, v165, v107
	v_mul_f32_e32 v166, v166, v107
	v_mul_f32_e32 v167, v167, v107
	v_mul_f32_e32 v180, v180, v108
	v_mul_f32_e32 v181, v181, v108
	v_mul_f32_e32 v182, v182, v108
	v_mul_f32_e32 v183, v183, v108
	v_mul_f32_e32 v196, v196, v109
	v_mul_f32_e32 v197, v197, v109
	v_mul_f32_e32 v198, v198, v109
	v_mul_f32_e32 v199, v199, v109
	v_mul_f32_e32 v148, v148, v12
	v_mul_f32_e32 v149, v149, v13
	v_mul_f32_e32 v150, v150, v14
	v_mul_f32_e32 v151, v151, v15
	v_mul_f32_e32 v164, v164, v12
	v_mul_f32_e32 v165, v165, v13
	v_mul_f32_e32 v166, v166, v14
	v_mul_f32_e32 v167, v167, v15
	v_mul_f32_e32 v180, v180, v12
	v_mul_f32_e32 v181, v181, v13
	v_mul_f32_e32 v182, v182, v14
	v_mul_f32_e32 v183, v183, v15
	v_mul_f32_e32 v196, v196, v12
	v_mul_f32_e32 v197, v197, v13
	v_mul_f32_e32 v198, v198, v14
	v_mul_f32_e32 v199, v199, v15
	v_cvt_pk_bf16_f32 v134, v148, v149
	v_cvt_pk_bf16_f32 v135, v150, v151
	v_cvt_pk_bf16_f32 v136, v164, v165
	v_cvt_pk_bf16_f32 v137, v166, v167
	v_cvt_pk_bf16_f32 v242, v180, v181
	v_cvt_pk_bf16_f32 v243, v182, v183
	v_cvt_pk_bf16_f32 v244, v196, v197
	v_cvt_pk_bf16_f32 v245, v198, v199
	global_store_dwordx2 v[126:127], v[134:135], off offset:1024
	global_store_dwordx2 v[128:129], v[136:137], off offset:1024
	global_store_dwordx2 v[130:131], v[242:243], off offset:1024
	global_store_dwordx2 v[132:133], v[244:245], off offset:1024
	s_nop 1
	v_mul_f32_e32 v152, v152, v106
	v_mul_f32_e32 v153, v153, v106
	v_mul_f32_e32 v154, v154, v106
	v_mul_f32_e32 v155, v155, v106
	v_mul_f32_e32 v168, v168, v107
	v_mul_f32_e32 v169, v169, v107
	v_mul_f32_e32 v170, v170, v107
	v_mul_f32_e32 v171, v171, v107
	v_mul_f32_e32 v184, v184, v108
	v_mul_f32_e32 v185, v185, v108
	v_mul_f32_e32 v186, v186, v108
	v_mul_f32_e32 v187, v187, v108
	v_mul_f32_e32 v200, v200, v109
	v_mul_f32_e32 v201, v201, v109
	v_mul_f32_e32 v202, v202, v109
	v_mul_f32_e32 v203, v203, v109
	v_mul_f32_e32 v152, v152, v16
	v_mul_f32_e32 v153, v153, v17
	v_mul_f32_e32 v154, v154, v18
	v_mul_f32_e32 v155, v155, v19
	v_mul_f32_e32 v168, v168, v16
	v_mul_f32_e32 v169, v169, v17
	v_mul_f32_e32 v170, v170, v18
	v_mul_f32_e32 v171, v171, v19
	v_mul_f32_e32 v184, v184, v16
	v_mul_f32_e32 v185, v185, v17
	v_mul_f32_e32 v186, v186, v18
	v_mul_f32_e32 v187, v187, v19
	v_mul_f32_e32 v200, v200, v16
	v_mul_f32_e32 v201, v201, v17
	v_mul_f32_e32 v202, v202, v18
	v_mul_f32_e32 v203, v203, v19
	v_cvt_pk_bf16_f32 v134, v152, v153
	v_cvt_pk_bf16_f32 v135, v154, v155
	v_cvt_pk_bf16_f32 v136, v168, v169
	v_cvt_pk_bf16_f32 v137, v170, v171
	v_cvt_pk_bf16_f32 v242, v184, v185
	v_cvt_pk_bf16_f32 v243, v186, v187
	v_cvt_pk_bf16_f32 v244, v200, v201
	v_cvt_pk_bf16_f32 v245, v202, v203
	global_store_dwordx2 v[126:127], v[134:135], off offset:1536
	global_store_dwordx2 v[128:129], v[136:137], off offset:1536
	global_store_dwordx2 v[130:131], v[242:243], off offset:1536
	global_store_dwordx2 v[132:133], v[244:245], off offset:1536
	s_add_i32 s61, s61, s34
	s_cmpk_gt_i32 s61, 0xff
	s_barrier
	s_cbranch_scc1 .LBB0_657
; #define KIN(i) (*(const float* const __attribute__((address_space(4)))*)(kp + kz + 8 * (i)))
; __global__ void __launch_bounds__(NTHR, 2) fwd_megakernel(Args args) {
;     ...
;         for (int cu = bid; cu < T / 32; cu += G) {
;             const int t0 = cu * 32, tb = (t0 / SEQ) * SEQ;
;             f32x2 wk[31];
; #pragma unroll
;             for (int k = 0; k < 31; ++k) wk[k] = *(const f32x2*)(KIN(I_CONV_W) + k * CCH + 2 * tid);
;             const f32x2 cb = *(const f32x2*)(KIN(I_CONV_B) + 2 * tid);
.LBB0_563:
	global_load_dwordx2 v[0:1], v[20:21], off
	global_load_dwordx2 v[2:3], v[34:35], off
	global_load_dwordx2 v[4:5], v[36:37], off
	global_load_dwordx2 v[6:7], v[38:39], off
	global_load_dwordx2 v[8:9], v[40:41], off
	global_load_dwordx2 v[10:11], v[42:43], off
	global_load_dwordx2 v[12:13], v[44:45], off
	global_load_dwordx2 v[14:15], v[46:47], off
	global_load_dwordx2 v[16:17], v[48:49], off
	global_load_dwordx2 v[18:19], v[50:51], off
	global_load_dwordx2 v[94:95], v[52:53], off
	global_load_dwordx2 v[96:97], v[54:55], off
	global_load_dwordx2 v[98:99], v[56:57], off
	global_load_dwordx2 v[100:101], v[58:59], off
	global_load_dwordx2 v[102:103], v[60:61], off
	global_load_dwordx2 v[104:105], v[62:63], off
	global_load_dwordx2 v[106:107], v[64:65], off
	global_load_dwordx2 v[108:109], v[66:67], off
	global_load_dwordx2 v[110:111], v[68:69], off
	global_load_dwordx2 v[112:113], v[70:71], off
	global_load_dwordx2 v[114:115], v[72:73], off
	global_load_dwordx2 v[116:117], v[74:75], off
	global_load_dwordx2 v[118:119], v[76:77], off
	global_load_dwordx2 v[120:121], v[78:79], off
	global_load_dwordx2 v[122:123], v[80:81], off
	global_load_dwordx2 v[124:125], v[82:83], off
	global_load_dwordx2 v[126:127], v[84:85], off
	global_load_dwordx2 v[128:129], v[86:87], off
	global_load_dwordx2 v[130:131], v[88:89], off
	global_load_dwordx2 v[132:133], v[90:91], off
	global_load_dwordx2 v[134:135], v[92:93], off
	global_load_dwordx2 v[136:137], v[22:23], off
	s_and_b32 s2, s95, 3
	s_lshl_b32 s2, s2, 10
	s_mov_b32 s3, 0
	s_cmp_lt_u32 s95, 4
	s_cselect_b64 vcc, -1, 0
	v_cndmask_b32_e32 v246, v28, v26, vcc
	v_cndmask_b32_e32 v247, v29, v27, vcc
	v_lshl_add_u64 v[246:247], v[246:247], 0, s[2:3]
	v_lshl_add_u64 v[250:251], v[30:31], 0, s[2:3]
	global_load_dwordx4 v[246:249], v[246:247], off
	global_load_dwordx4 v[250:253], v[250:251], off
	s_ashr_i32 s2, s61, 31
	s_lshr_b32 s2, s2, 25
	s_add_i32 s2, s61, s2
	s_lshl_b32 s2, s2, 5
	s_lshl_b32 s62, s61, 5
	s_and_b32 s11, s2, 0xfffff000
	s_mov_b64 s[4:5], -1
	s_mov_b32 s63, 0
	s_branch .LBB0_565
